# P3 ctx-DFT tile epilogue: 16 serialized load/store round trips replaced by one batch of loads
# speedup vs baseline: 1.0010x; 1.0010x over previous
; template <bool TRANS, class Epi>
; DEVI void gemm_tile(const bf16_t* __restrict__ A0, const bf16_t* __restrict__ A1, int ksplit, int lda,
;                     const bf16_t* __restrict__ Bt, int ldb, int nk, char* smem, const Epi& epi, int row0, int col0) {
;     ...
;     auto issue = [&](int kt, int buf) {
;         const bf16_t* ap = (kt < ksplit ? A0 + (size_t)kt * 64 : A1 + (size_t)(kt - ksplit) * 64) + aoff;
;         const bf16_t* bp = Bt + (size_t)kt * 64 + boff;
;         char* sa = smem + buf * 32768 + ldsoff;
;         char* sb = sa + 16384;
; #pragma unroll
;         for (int i = 0; i < 4; ++i) __builtin_amdgcn_global_load_lds((const unsigned*)(ap + (size_t)(32 * i) * lda), (unsigned*)(sa + i * 4096), 16, 0, 0);
; #pragma unroll
;         for (int i = 0; i < 4; ++i) __builtin_amdgcn_global_load_lds((const unsigned*)(bp + (size_t)(32 * i) * ldb), (unsigned*)(sb + i * 4096), 16, 0, 0);
;     };
;     __syncthreads();
;     issue(0, 0);
;     asm volatile("s_waitcnt vmcnt(0)" ::: "memory");
;     __syncthreads();
;     for (int kt = 0; kt < nk; ++kt) {
;         const int buf = kt & 1;
;         if (kt + 1 < nk) issue(kt + 1, buf ^ 1);
;         const char* sa = smem + buf * 32768;
;         const char* sb = sa + 16384;
; #pragma unroll
;         for (int kk = 0; kk < 2; ++kk) {
;             bf16x8 af[4], bfr[4];
;             const int cho = (((kk * 4 + fq) ^ (fr & 7)) << 4);
; #pragma unroll
;             for (int m = 0; m < 4; ++m) af[m] = *(const bf16x8*)(sa + (wr * 64 + 16 * m + fr) * 128 + cho);
; #pragma unroll
;             for (int n = 0; n < 4; ++n) bfr[n] = *(const bf16x8*)(sb + (wc * 64 + 16 * n + fr) * 128 + cho);
;             __builtin_amdgcn_s_setprio(1);
; #pragma unroll
;             for (int m = 0; m < 4; ++m)
; #pragma unroll
;                 for (int n = 0; n < 4; ++n)
;                     acc[m][n] = TRANS ? __builtin_amdgcn_mfma_f32_16x16x32_bf16(bfr[n], af[m], acc[m][n], 0, 0, 0)
;                                       : __builtin_amdgcn_mfma_f32_16x16x32_bf16(af[m], bfr[n], acc[m][n], 0, 0, 0);
;             __builtin_amdgcn_s_setprio(0);
;         }
;         asm volatile("s_waitcnt vmcnt(0)" ::: "memory");
;         __syncthreads();
.LBB0_596:
	s_bfe_u32 s5, s33, 0x10003
	s_ashr_i32 s4, s33, 4
	s_lshl_b32 s0, s5, 17
	s_add_u32 s0, vcc_lo, s0
	s_waitcnt vmcnt(0)
	v_mov_b32_e32 v6, v172
	s_addc_u32 s1, vcc_hi, 0
	s_lshl_b32 s2, s4, 10
	s_and_b32 s82, s80, 0x380
	s_or_b32 s2, s2, s82
	v_ashrrev_i32_e32 v3, 6, v6
	s_waitcnt lgkmcnt(0)
	v_bfe_u32 v1, v6, 3, 3
	v_and_b32_e32 v2, 63, v6
	v_lshl_or_b32 v0, v3, 3, v1
	s_ashr_i32 s3, s2, 31
	v_bitop3_b32 v4, v1, v6, 7 bitop3:0x78
	v_ashrrev_i32_e32 v1, 31, v0
	v_lshlrev_b32_e32 v5, 10, v3
	v_lshlrev_b32_e32 v8, 4, v2
	s_lshl_b64 s[2:3], s[2:3], 10
	v_and_b32_e32 v51, 1, v3
	v_lshlrev_b64 v[2:3], 10, v[0:1]
	v_add3_u32 v14, 0, v5, v8
	s_add_u32 s2, s10, s2
	v_lshl_or_b32 v2, v4, 4, v2
	v_readfirstlane_b32 s19, v14
	v_add_u32_e32 v8, 0x1000, v14
	s_addc_u32 s3, s11, s3
	s_mulk_i32 s4, 0x1100
	s_lshl_b32 s5, s5, 7
	v_lshl_add_u64 v[0:1], s[0:1], 0, v[2:3]
	s_mov_b32 m0, s19
	s_mov_b64 s[0:1], 0x8000
	v_readfirstlane_b32 s26, v8
	v_add_u32_e32 v8, 0x2000, v14
	s_or_b32 s9, s5, s4
	s_barrier
	global_load_lds_dwordx4 v[0:1], off
	v_lshl_add_u64 v[4:5], v[0:1], 0, s[0:1]
	s_mov_b32 m0, s26
	s_mov_b64 s[4:5], 0x10000
	v_readfirstlane_b32 s83, v8
	v_add_u32_e32 v8, 0x3000, v14
	global_load_lds_dwordx4 v[4:5], off
	v_lshl_add_u64 v[4:5], v[0:1], 0, s[4:5]
	s_mov_b32 m0, s83
	s_mov_b64 s[6:7], 0x18000
	v_readfirstlane_b32 s18, v8
	global_load_lds_dwordx4 v[4:5], off
	v_lshl_add_u64 v[4:5], v[0:1], 0, s[6:7]
	s_mov_b32 m0, s18
	v_lshl_add_u64 v[2:3], s[2:3], 0, v[2:3]
	global_load_lds_dwordx4 v[4:5], off
	v_add_u32_e32 v4, 0x4000, v14
	v_add_u32_e32 v8, 0x5000, v14
	v_readfirstlane_b32 s77, v4
	s_mov_b32 m0, s77
	v_lshl_add_u64 v[4:5], v[2:3], 0, s[0:1]
	v_readfirstlane_b32 s0, v8
	v_add_u32_e32 v8, 0x6000, v14
	global_load_lds_dwordx4 v[2:3], off
	s_mov_b32 m0, s0
	v_readfirstlane_b32 s1, v8
	v_add_u32_e32 v8, 0x7000, v14
	global_load_lds_dwordx4 v[4:5], off
	v_lshl_add_u64 v[4:5], v[2:3], 0, s[4:5]
	s_mov_b32 m0, s1
	v_readfirstlane_b32 s2, v8
	v_add_u32_e32 v8, 0x8000, v14
	global_load_lds_dwordx4 v[4:5], off
	v_lshl_add_u64 v[4:5], v[2:3], 0, s[6:7]
	s_mov_b32 m0, s2
	s_mov_b64 s[44:45], 0x80
	v_readfirstlane_b32 s6, v8
	v_add_u32_e32 v9, 0x9000, v14
	global_load_lds_dwordx4 v[4:5], off
	v_lshl_add_u64 v[4:5], v[0:1], 0, s[44:45]
	s_mov_b32 m0, s6
	s_mov_b64 s[12:13], 0x8080
	v_readfirstlane_b32 s3, v9
	v_add_u32_e32 v10, 0xa000, v14
	s_waitcnt vmcnt(0)
	s_waitcnt vmcnt(0) lgkmcnt(0)
	s_barrier
	global_load_lds_dwordx4 v[4:5], off
	v_lshl_add_u64 v[4:5], v[0:1], 0, s[12:13]
	s_mov_b32 m0, s3
	s_mov_b64 s[16:17], 0x10080
	v_readfirstlane_b32 s4, v10
	v_add_u32_e32 v11, 0xb000, v14
	global_load_lds_dwordx4 v[4:5], off
	v_lshl_add_u64 v[4:5], v[0:1], 0, s[16:17]
	s_mov_b32 m0, s4
	v_readfirstlane_b32 s5, v11
	v_add_u32_e32 v12, 0xc000, v14
	global_load_lds_dwordx4 v[4:5], off
	v_lshl_add_u64 v[4:5], v[0:1], 0, s[20:21]
	s_mov_b32 m0, s5
	v_readfirstlane_b32 s7, v12
	v_add_u32_e32 v13, 0xd000, v14
	global_load_lds_dwordx4 v[4:5], off
	v_lshl_add_u64 v[4:5], v[2:3], 0, s[44:45]
	s_mov_b32 m0, s7
	v_readfirstlane_b32 s8, v13
	v_add_u32_e32 v15, 0xe000, v14
	global_load_lds_dwordx4 v[4:5], off
	v_lshl_add_u64 v[4:5], v[2:3], 0, s[12:13]
	s_mov_b32 m0, s8
	v_readfirstlane_b32 s44, v15
	v_add_u32_e32 v14, 0xf000, v14
	global_load_lds_dwordx4 v[4:5], off
	v_lshl_add_u64 v[4:5], v[2:3], 0, s[16:17]
	s_mov_b32 m0, s44
	v_readfirstlane_b32 s45, v14
	global_load_lds_dwordx4 v[4:5], off
	v_lshl_add_u64 v[4:5], v[2:3], 0, s[20:21]
	s_mov_b32 m0, s45
	v_and_b32_e32 v50, 15, v6
	global_load_lds_dwordx4 v[4:5], off
	v_bfe_u32 v52, v6, 4, 2
	v_ashrrev_i32_e32 v48, 7, v6
	v_and_b32_e32 v7, 7, v6
	v_bitop3_b32 v4, v52, v6, 7 bitop3:0x78
	v_lshlrev_b32_e32 v6, 7, v50
	v_lshl_add_u32 v5, v4, 4, 0
	v_lshl_or_b32 v46, v48, 13, v6
	v_lshl_or_b32 v47, v51, 13, v6
	v_add_u32_e32 v4, v5, v46
	v_add_u32_e32 v5, v5, v47
	ds_read_b128 v[14:17], v4
	ds_read_b128 v[18:21], v4 offset:2048
	ds_read_b128 v[22:25], v4 offset:4096
	ds_read_b128 v[26:29], v4 offset:6144
	ds_read_b128 v[30:33], v5 offset:16384
	ds_read_b128 v[34:37], v5 offset:18432
	ds_read_b128 v[38:41], v5 offset:20480
	ds_read_b128 v[42:45], v5 offset:22528
	s_setprio 1
	s_waitcnt lgkmcnt(0)
	v_mfma_f32_16x16x32_bf16 v[54:57], v[30:33], v[14:17], 0
	v_mfma_f32_16x16x32_bf16 v[58:61], v[34:37], v[14:17], 0
	v_mfma_f32_16x16x32_bf16 v[62:65], v[38:41], v[14:17], 0
	v_mfma_f32_16x16x32_bf16 v[14:17], v[42:45], v[14:17], 0
	v_mfma_f32_16x16x32_bf16 v[66:69], v[30:33], v[18:21], 0
	v_mfma_f32_16x16x32_bf16 v[70:73], v[34:37], v[18:21], 0
	v_mfma_f32_16x16x32_bf16 v[74:77], v[38:41], v[18:21], 0
	v_mfma_f32_16x16x32_bf16 v[18:21], v[42:45], v[18:21], 0
	v_mfma_f32_16x16x32_bf16 v[78:81], v[30:33], v[22:25], 0
	v_mfma_f32_16x16x32_bf16 v[82:85], v[34:37], v[22:25], 0
	v_mfma_f32_16x16x32_bf16 v[86:89], v[38:41], v[22:25], 0
	v_mfma_f32_16x16x32_bf16 v[22:25], v[42:45], v[22:25], 0
	v_mfma_f32_16x16x32_bf16 v[30:33], v[30:33], v[26:29], 0
	v_mfma_f32_16x16x32_bf16 v[34:37], v[34:37], v[26:29], 0
	v_mfma_f32_16x16x32_bf16 v[38:41], v[38:41], v[26:29], 0
	v_mfma_f32_16x16x32_bf16 v[26:29], v[42:45], v[26:29], 0
	s_setprio 0
	v_bitop3_b32 v6, v52, v7, 4 bitop3:0x36
	v_lshl_add_u32 v7, v6, 4, 0
	v_add_u32_e32 v6, v7, v46
	v_add_u32_e32 v7, v7, v47
	ds_read_b128 v[42:45], v6
	ds_read_b128 v[90:93], v6 offset:2048
	ds_read_b128 v[94:97], v6 offset:4096
	ds_read_b128 v[98:101], v6 offset:6144
	ds_read_b128 v[102:105], v7 offset:16384
	ds_read_b128 v[106:109], v7 offset:18432
	ds_read_b128 v[110:113], v7 offset:20480
	ds_read_b128 v[114:117], v7 offset:22528
	s_setprio 1
	s_waitcnt lgkmcnt(0)
	v_mfma_f32_16x16x32_bf16 v[54:57], v[102:105], v[42:45], v[54:57]
	v_mfma_f32_16x16x32_bf16 v[58:61], v[106:109], v[42:45], v[58:61]
	v_mfma_f32_16x16x32_bf16 v[62:65], v[110:113], v[42:45], v[62:65]
	v_mfma_f32_16x16x32_bf16 v[14:17], v[114:117], v[42:45], v[14:17]
	v_mfma_f32_16x16x32_bf16 v[42:45], v[102:105], v[90:93], v[66:69]
	v_mfma_f32_16x16x32_bf16 v[66:69], v[106:109], v[90:93], v[70:73]
	v_mfma_f32_16x16x32_bf16 v[70:73], v[110:113], v[90:93], v[74:77]
	v_mfma_f32_16x16x32_bf16 v[18:21], v[114:117], v[90:93], v[18:21]
	v_mfma_f32_16x16x32_bf16 v[74:77], v[102:105], v[94:97], v[78:81]
	v_mfma_f32_16x16x32_bf16 v[78:81], v[106:109], v[94:97], v[82:85]
	v_mfma_f32_16x16x32_bf16 v[82:85], v[110:113], v[94:97], v[86:89]
	v_mfma_f32_16x16x32_bf16 v[22:25], v[114:117], v[94:97], v[22:25]
	v_mfma_f32_16x16x32_bf16 v[30:33], v[102:105], v[98:101], v[30:33]
	v_mfma_f32_16x16x32_bf16 v[34:37], v[106:109], v[98:101], v[34:37]
	v_mfma_f32_16x16x32_bf16 v[38:41], v[110:113], v[98:101], v[38:41]
	v_mfma_f32_16x16x32_bf16 v[26:29], v[114:117], v[98:101], v[26:29]
	s_setprio 0
	s_mov_b64 s[12:13], 0x100
	s_mov_b32 m0, s19
	v_lshl_add_u64 v[46:47], v[0:1], 0, s[12:13]
	s_mov_b64 s[16:17], 0x8100
	s_waitcnt vmcnt(0)
	s_waitcnt vmcnt(0)
	s_barrier
; template <bool TRANS, class Epi>
; DEVI void gemm_tile(const bf16_t* __restrict__ A0, const bf16_t* __restrict__ A1, int ksplit, int lda,
;                     const bf16_t* __restrict__ Bt, int ldb, int nk, char* smem, const Epi& epi, int row0, int col0) {
;     ...
;     auto issue = [&](int kt, int buf) {
;         const bf16_t* ap = (kt < ksplit ? A0 + (size_t)kt * 64 : A1 + (size_t)(kt - ksplit) * 64) + aoff;
;         const bf16_t* bp = Bt + (size_t)kt * 64 + boff;
;         char* sa = smem + buf * 32768 + ldsoff;
;         char* sb = sa + 16384;
; #pragma unroll
;         for (int i = 0; i < 4; ++i) __builtin_amdgcn_global_load_lds((const unsigned*)(ap + (size_t)(32 * i) * lda), (unsigned*)(sa + i * 4096), 16, 0, 0);
; #pragma unroll
;         for (int i = 0; i < 4; ++i) __builtin_amdgcn_global_load_lds((const unsigned*)(bp + (size_t)(32 * i) * ldb), (unsigned*)(sb + i * 4096), 16, 0, 0);
;     };
;     __syncthreads();
;     issue(0, 0);
;     asm volatile("s_waitcnt vmcnt(0)" ::: "memory");
;     __syncthreads();
;     for (int kt = 0; kt < nk; ++kt) {
;         const int buf = kt & 1;
;         if (kt + 1 < nk) issue(kt + 1, buf ^ 1);
;         const char* sa = smem + buf * 32768;
;         const char* sb = sa + 16384;
; #pragma unroll
;         for (int kk = 0; kk < 2; ++kk) {
;             bf16x8 af[4], bfr[4];
;             const int cho = (((kk * 4 + fq) ^ (fr & 7)) << 4);
; #pragma unroll
;             for (int m = 0; m < 4; ++m) af[m] = *(const bf16x8*)(sa + (wr * 64 + 16 * m + fr) * 128 + cho);
; #pragma unroll
;             for (int n = 0; n < 4; ++n) bfr[n] = *(const bf16x8*)(sb + (wc * 64 + 16 * n + fr) * 128 + cho);
;             __builtin_amdgcn_s_setprio(1);
; #pragma unroll
;             for (int m = 0; m < 4; ++m)
; #pragma unroll
;                 for (int n = 0; n < 4; ++n)
;                     acc[m][n] = TRANS ? __builtin_amdgcn_mfma_f32_16x16x32_bf16(bfr[n], af[m], acc[m][n], 0, 0, 0)
;                                       : __builtin_amdgcn_mfma_f32_16x16x32_bf16(af[m], bfr[n], acc[m][n], 0, 0, 0);
;             __builtin_amdgcn_s_setprio(0);
;         }
;         asm volatile("s_waitcnt vmcnt(0)" ::: "memory");
;         __syncthreads();
	global_load_lds_dwordx4 v[46:47], off
	v_lshl_add_u64 v[46:47], v[0:1], 0, s[16:17]
	s_mov_b32 m0, s26
	s_nop 0
	global_load_lds_dwordx4 v[46:47], off
	v_lshl_add_u64 v[46:47], v[0:1], 0, s[24:25]
	s_mov_b32 m0, s83
	s_nop 0
	global_load_lds_dwordx4 v[46:47], off
	v_lshl_add_u64 v[46:47], v[0:1], 0, s[28:29]
	s_mov_b32 m0, s18
	s_nop 0
	global_load_lds_dwordx4 v[46:47], off
	v_lshl_add_u64 v[46:47], v[2:3], 0, s[12:13]
	s_mov_b32 m0, s77
	s_nop 0
	global_load_lds_dwordx4 v[46:47], off
	v_lshl_add_u64 v[46:47], v[2:3], 0, s[16:17]
	s_mov_b32 m0, s0
	s_nop 0
	global_load_lds_dwordx4 v[46:47], off
	v_lshl_add_u64 v[46:47], v[2:3], 0, s[24:25]
	s_mov_b32 m0, s1
	s_nop 0
	global_load_lds_dwordx4 v[46:47], off
	v_lshl_add_u64 v[46:47], v[2:3], 0, s[28:29]
	s_mov_b32 m0, s2
	s_nop 0
	global_load_lds_dwordx4 v[46:47], off
	ds_read_b128 v[86:89], v4 offset:32768
	ds_read_b128 v[90:93], v4 offset:34816
	ds_read_b128 v[94:97], v4 offset:36864
	ds_read_b128 v[98:101], v4 offset:38912
	ds_read_b128 v[102:105], v5 offset:49152
	ds_read_b128 v[106:109], v5 offset:51200
	ds_read_b128 v[110:113], v5 offset:53248
	ds_read_b128 v[114:117], v5 offset:55296
	s_setprio 1
	s_waitcnt lgkmcnt(0)
	v_mfma_f32_16x16x32_bf16 v[54:57], v[102:105], v[86:89], v[54:57]
	v_mfma_f32_16x16x32_bf16 v[58:61], v[106:109], v[86:89], v[58:61]
	v_mfma_f32_16x16x32_bf16 v[62:65], v[110:113], v[86:89], v[62:65]
	v_mfma_f32_16x16x32_bf16 v[14:17], v[114:117], v[86:89], v[14:17]
	v_mfma_f32_16x16x32_bf16 v[42:45], v[102:105], v[90:93], v[42:45]
	v_mfma_f32_16x16x32_bf16 v[66:69], v[106:109], v[90:93], v[66:69]
	v_mfma_f32_16x16x32_bf16 v[70:73], v[110:113], v[90:93], v[70:73]
	v_mfma_f32_16x16x32_bf16 v[18:21], v[114:117], v[90:93], v[18:21]
	v_mfma_f32_16x16x32_bf16 v[74:77], v[102:105], v[94:97], v[74:77]
	v_mfma_f32_16x16x32_bf16 v[78:81], v[106:109], v[94:97], v[78:81]
	v_mfma_f32_16x16x32_bf16 v[82:85], v[110:113], v[94:97], v[82:85]
	v_mfma_f32_16x16x32_bf16 v[22:25], v[114:117], v[94:97], v[22:25]
	v_mfma_f32_16x16x32_bf16 v[30:33], v[102:105], v[98:101], v[30:33]
	v_mfma_f32_16x16x32_bf16 v[34:37], v[106:109], v[98:101], v[34:37]
	v_mfma_f32_16x16x32_bf16 v[38:41], v[110:113], v[98:101], v[38:41]
	v_mfma_f32_16x16x32_bf16 v[26:29], v[114:117], v[98:101], v[26:29]
	s_setprio 0
	ds_read_b128 v[86:89], v6 offset:32768
	ds_read_b128 v[90:93], v6 offset:34816
	ds_read_b128 v[94:97], v6 offset:36864
	ds_read_b128 v[98:101], v6 offset:38912
	ds_read_b128 v[102:105], v7 offset:49152
	ds_read_b128 v[106:109], v7 offset:51200
	ds_read_b128 v[110:113], v7 offset:53248
	ds_read_b128 v[114:117], v7 offset:55296
	s_setprio 1
	s_waitcnt lgkmcnt(0)
	v_mfma_f32_16x16x32_bf16 v[54:57], v[102:105], v[86:89], v[54:57]
	v_mfma_f32_16x16x32_bf16 v[58:61], v[106:109], v[86:89], v[58:61]
	v_mfma_f32_16x16x32_bf16 v[62:65], v[110:113], v[86:89], v[62:65]
	v_mfma_f32_16x16x32_bf16 v[14:17], v[114:117], v[86:89], v[14:17]
	v_mfma_f32_16x16x32_bf16 v[42:45], v[102:105], v[90:93], v[42:45]
	v_mfma_f32_16x16x32_bf16 v[66:69], v[106:109], v[90:93], v[66:69]
	v_mfma_f32_16x16x32_bf16 v[70:73], v[110:113], v[90:93], v[70:73]
	v_mfma_f32_16x16x32_bf16 v[18:21], v[114:117], v[90:93], v[18:21]
	v_mfma_f32_16x16x32_bf16 v[74:77], v[102:105], v[94:97], v[74:77]
	v_mfma_f32_16x16x32_bf16 v[78:81], v[106:109], v[94:97], v[78:81]
	v_mfma_f32_16x16x32_bf16 v[82:85], v[110:113], v[94:97], v[82:85]
	v_mfma_f32_16x16x32_bf16 v[22:25], v[114:117], v[94:97], v[22:25]
	v_mfma_f32_16x16x32_bf16 v[30:33], v[102:105], v[98:101], v[30:33]
	v_mfma_f32_16x16x32_bf16 v[34:37], v[106:109], v[98:101], v[34:37]
	v_mfma_f32_16x16x32_bf16 v[38:41], v[110:113], v[98:101], v[38:41]
	v_mfma_f32_16x16x32_bf16 v[26:29], v[114:117], v[98:101], v[26:29]
	s_setprio 0
	s_mov_b32 m0, s6
	v_lshl_add_u64 v[46:47], v[0:1], 0, s[30:31]
	s_waitcnt vmcnt(0)
	s_waitcnt vmcnt(0)
	s_barrier
	global_load_lds_dwordx4 v[46:47], off
	v_lshl_add_u64 v[46:47], v[0:1], 0, s[58:59]
	s_mov_b32 m0, s3
	s_nop 0
	global_load_lds_dwordx4 v[46:47], off
	v_lshl_add_u64 v[46:47], v[0:1], 0, s[60:61]
	s_mov_b32 m0, s4
	s_nop 0
	global_load_lds_dwordx4 v[46:47], off
	v_lshl_add_u64 v[46:47], v[0:1], 0, s[62:63]
	s_mov_b32 m0, s5
	s_nop 0
	global_load_lds_dwordx4 v[46:47], off
	v_lshl_add_u64 v[46:47], v[2:3], 0, s[30:31]
	s_mov_b32 m0, s7
	s_nop 0
	global_load_lds_dwordx4 v[46:47], off
	v_lshl_add_u64 v[46:47], v[2:3], 0, s[58:59]
	s_mov_b32 m0, s8
	s_nop 0
	global_load_lds_dwordx4 v[46:47], off
	v_lshl_add_u64 v[46:47], v[2:3], 0, s[60:61]
	s_mov_b32 m0, s44
	s_nop 0
	global_load_lds_dwordx4 v[46:47], off
	v_lshl_add_u64 v[46:47], v[2:3], 0, s[62:63]
	s_mov_b32 m0, s45
	s_nop 0
	global_load_lds_dwordx4 v[46:47], off
	ds_read_b128 v[86:89], v4
	ds_read_b128 v[90:93], v4 offset:2048
	ds_read_b128 v[94:97], v4 offset:4096
	ds_read_b128 v[98:101], v4 offset:6144
	ds_read_b128 v[102:105], v5 offset:16384
	ds_read_b128 v[106:109], v5 offset:18432
	ds_read_b128 v[110:113], v5 offset:20480
	ds_read_b128 v[114:117], v5 offset:22528
	s_setprio 1
	s_waitcnt lgkmcnt(0)
; template <bool TRANS, class Epi>
; DEVI void gemm_tile(const bf16_t* __restrict__ A0, const bf16_t* __restrict__ A1, int ksplit, int lda,
;                     const bf16_t* __restrict__ Bt, int ldb, int nk, char* smem, const Epi& epi, int row0, int col0) {
;     ...
;     auto issue = [&](int kt, int buf) {
;         const bf16_t* ap = (kt < ksplit ? A0 + (size_t)kt * 64 : A1 + (size_t)(kt - ksplit) * 64) + aoff;
;         const bf16_t* bp = Bt + (size_t)kt * 64 + boff;
;         char* sa = smem + buf * 32768 + ldsoff;
;         char* sb = sa + 16384;
; #pragma unroll
;         for (int i = 0; i < 4; ++i) __builtin_amdgcn_global_load_lds((const unsigned*)(ap + (size_t)(32 * i) * lda), (unsigned*)(sa + i * 4096), 16, 0, 0);
; #pragma unroll
;         for (int i = 0; i < 4; ++i) __builtin_amdgcn_global_load_lds((const unsigned*)(bp + (size_t)(32 * i) * ldb), (unsigned*)(sb + i * 4096), 16, 0, 0);
;     };
;     __syncthreads();
;     issue(0, 0);
;     asm volatile("s_waitcnt vmcnt(0)" ::: "memory");
;     __syncthreads();
;     for (int kt = 0; kt < nk; ++kt) {
;         const int buf = kt & 1;
;         if (kt + 1 < nk) issue(kt + 1, buf ^ 1);
;         const char* sa = smem + buf * 32768;
;         const char* sb = sa + 16384;
; #pragma unroll
;         for (int kk = 0; kk < 2; ++kk) {
;             bf16x8 af[4], bfr[4];
;             const int cho = (((kk * 4 + fq) ^ (fr & 7)) << 4);
; #pragma unroll
;             for (int m = 0; m < 4; ++m) af[m] = *(const bf16x8*)(sa + (wr * 64 + 16 * m + fr) * 128 + cho);
; #pragma unroll
;             for (int n = 0; n < 4; ++n) bfr[n] = *(const bf16x8*)(sb + (wc * 64 + 16 * n + fr) * 128 + cho);
;             __builtin_amdgcn_s_setprio(1);
; #pragma unroll
;             for (int m = 0; m < 4; ++m)
; #pragma unroll
;                 for (int n = 0; n < 4; ++n)
;                     acc[m][n] = TRANS ? __builtin_amdgcn_mfma_f32_16x16x32_bf16(bfr[n], af[m], acc[m][n], 0, 0, 0)
;                                       : __builtin_amdgcn_mfma_f32_16x16x32_bf16(af[m], bfr[n], acc[m][n], 0, 0, 0);
;             __builtin_amdgcn_s_setprio(0);
;         }
;         asm volatile("s_waitcnt vmcnt(0)" ::: "memory");
;         __syncthreads();
	v_mfma_f32_16x16x32_bf16 v[54:57], v[102:105], v[86:89], v[54:57]
	v_mfma_f32_16x16x32_bf16 v[58:61], v[106:109], v[86:89], v[58:61]
	v_mfma_f32_16x16x32_bf16 v[62:65], v[110:113], v[86:89], v[62:65]
	v_mfma_f32_16x16x32_bf16 v[14:17], v[114:117], v[86:89], v[14:17]
	v_mfma_f32_16x16x32_bf16 v[42:45], v[102:105], v[90:93], v[42:45]
	v_mfma_f32_16x16x32_bf16 v[66:69], v[106:109], v[90:93], v[66:69]
	v_mfma_f32_16x16x32_bf16 v[70:73], v[110:113], v[90:93], v[70:73]
	v_mfma_f32_16x16x32_bf16 v[18:21], v[114:117], v[90:93], v[18:21]
	v_mfma_f32_16x16x32_bf16 v[74:77], v[102:105], v[94:97], v[74:77]
	v_mfma_f32_16x16x32_bf16 v[78:81], v[106:109], v[94:97], v[78:81]
	v_mfma_f32_16x16x32_bf16 v[82:85], v[110:113], v[94:97], v[82:85]
	v_mfma_f32_16x16x32_bf16 v[22:25], v[114:117], v[94:97], v[22:25]
	v_mfma_f32_16x16x32_bf16 v[30:33], v[102:105], v[98:101], v[30:33]
	v_mfma_f32_16x16x32_bf16 v[34:37], v[106:109], v[98:101], v[34:37]
	v_mfma_f32_16x16x32_bf16 v[38:41], v[110:113], v[98:101], v[38:41]
	v_mfma_f32_16x16x32_bf16 v[26:29], v[114:117], v[98:101], v[26:29]
	s_setprio 0
	ds_read_b128 v[86:89], v6
	ds_read_b128 v[90:93], v6 offset:2048
	ds_read_b128 v[94:97], v6 offset:4096
	ds_read_b128 v[98:101], v6 offset:6144
	ds_read_b128 v[102:105], v7 offset:16384
	ds_read_b128 v[106:109], v7 offset:18432
	ds_read_b128 v[110:113], v7 offset:20480
	ds_read_b128 v[114:117], v7 offset:22528
	s_setprio 1
	s_waitcnt lgkmcnt(0)
	v_mfma_f32_16x16x32_bf16 v[54:57], v[102:105], v[86:89], v[54:57]
	v_mfma_f32_16x16x32_bf16 v[58:61], v[106:109], v[86:89], v[58:61]
	v_mfma_f32_16x16x32_bf16 v[62:65], v[110:113], v[86:89], v[62:65]
	v_mfma_f32_16x16x32_bf16 v[14:17], v[114:117], v[86:89], v[14:17]
	v_mfma_f32_16x16x32_bf16 v[42:45], v[102:105], v[90:93], v[42:45]
	v_mfma_f32_16x16x32_bf16 v[66:69], v[106:109], v[90:93], v[66:69]
	v_mfma_f32_16x16x32_bf16 v[70:73], v[110:113], v[90:93], v[70:73]
	v_mfma_f32_16x16x32_bf16 v[18:21], v[114:117], v[90:93], v[18:21]
	v_mfma_f32_16x16x32_bf16 v[74:77], v[102:105], v[94:97], v[74:77]
	v_mfma_f32_16x16x32_bf16 v[78:81], v[106:109], v[94:97], v[78:81]
	v_mfma_f32_16x16x32_bf16 v[82:85], v[110:113], v[94:97], v[82:85]
	v_mfma_f32_16x16x32_bf16 v[22:25], v[114:117], v[94:97], v[22:25]
	v_mfma_f32_16x16x32_bf16 v[30:33], v[102:105], v[98:101], v[30:33]
	v_mfma_f32_16x16x32_bf16 v[34:37], v[106:109], v[98:101], v[34:37]
	v_mfma_f32_16x16x32_bf16 v[38:41], v[110:113], v[98:101], v[38:41]
	v_mfma_f32_16x16x32_bf16 v[26:29], v[114:117], v[98:101], v[26:29]
	s_setprio 0
	s_mov_b32 m0, s19
	v_lshl_add_u64 v[46:47], v[0:1], 0, s[64:65]
	s_waitcnt vmcnt(0)
	s_waitcnt vmcnt(0)
	s_barrier
	global_load_lds_dwordx4 v[46:47], off
	v_lshl_add_u64 v[46:47], v[0:1], 0, s[68:69]
	s_mov_b32 m0, s26
	s_nop 0
	global_load_lds_dwordx4 v[46:47], off
	v_lshl_add_u64 v[46:47], v[0:1], 0, s[74:75]
	s_mov_b32 m0, s83
	s_nop 0
	global_load_lds_dwordx4 v[46:47], off
	v_lshl_add_u64 v[46:47], v[0:1], 0, s[78:79]
	s_mov_b32 m0, s18
	s_nop 0
	global_load_lds_dwordx4 v[46:47], off
	v_lshl_add_u64 v[46:47], v[2:3], 0, s[64:65]
	s_mov_b32 m0, s77
	s_nop 0
	global_load_lds_dwordx4 v[46:47], off
	v_lshl_add_u64 v[46:47], v[2:3], 0, s[68:69]
	s_mov_b32 m0, s0
	s_nop 0
	global_load_lds_dwordx4 v[46:47], off
	v_lshl_add_u64 v[46:47], v[2:3], 0, s[74:75]
	s_mov_b32 m0, s1
	s_nop 0
	global_load_lds_dwordx4 v[46:47], off
	v_lshl_add_u64 v[46:47], v[2:3], 0, s[78:79]
	s_mov_b32 m0, s2
	s_nop 0
	global_load_lds_dwordx4 v[46:47], off
	ds_read_b128 v[86:89], v4 offset:32768
	ds_read_b128 v[90:93], v4 offset:34816
	ds_read_b128 v[94:97], v4 offset:36864
	ds_read_b128 v[98:101], v4 offset:38912
	ds_read_b128 v[102:105], v5 offset:49152
	ds_read_b128 v[106:109], v5 offset:51200
	ds_read_b128 v[110:113], v5 offset:53248
	ds_read_b128 v[114:117], v5 offset:55296
	s_setprio 1
	s_waitcnt lgkmcnt(0)
	v_mfma_f32_16x16x32_bf16 v[54:57], v[102:105], v[86:89], v[54:57]
	v_mfma_f32_16x16x32_bf16 v[58:61], v[106:109], v[86:89], v[58:61]
	v_mfma_f32_16x16x32_bf16 v[62:65], v[110:113], v[86:89], v[62:65]
	v_mfma_f32_16x16x32_bf16 v[14:17], v[114:117], v[86:89], v[14:17]
	v_mfma_f32_16x16x32_bf16 v[42:45], v[102:105], v[90:93], v[42:45]
	v_mfma_f32_16x16x32_bf16 v[66:69], v[106:109], v[90:93], v[66:69]
	v_mfma_f32_16x16x32_bf16 v[70:73], v[110:113], v[90:93], v[70:73]
	v_mfma_f32_16x16x32_bf16 v[18:21], v[114:117], v[90:93], v[18:21]
	v_mfma_f32_16x16x32_bf16 v[74:77], v[102:105], v[94:97], v[74:77]
	v_mfma_f32_16x16x32_bf16 v[78:81], v[106:109], v[94:97], v[78:81]
	v_mfma_f32_16x16x32_bf16 v[82:85], v[110:113], v[94:97], v[82:85]
	v_mfma_f32_16x16x32_bf16 v[22:25], v[114:117], v[94:97], v[22:25]
	v_mfma_f32_16x16x32_bf16 v[30:33], v[102:105], v[98:101], v[30:33]
	v_mfma_f32_16x16x32_bf16 v[34:37], v[106:109], v[98:101], v[34:37]
	v_mfma_f32_16x16x32_bf16 v[38:41], v[110:113], v[98:101], v[38:41]
	v_mfma_f32_16x16x32_bf16 v[26:29], v[114:117], v[98:101], v[26:29]
	s_setprio 0
	ds_read_b128 v[86:89], v6 offset:32768
	ds_read_b128 v[90:93], v6 offset:34816
	ds_read_b128 v[94:97], v6 offset:36864
	ds_read_b128 v[98:101], v6 offset:38912
	ds_read_b128 v[102:105], v7 offset:49152
	ds_read_b128 v[106:109], v7 offset:51200
	ds_read_b128 v[110:113], v7 offset:53248
	ds_read_b128 v[114:117], v7 offset:55296
	s_setprio 1
	s_waitcnt lgkmcnt(0)
	v_mfma_f32_16x16x32_bf16 v[54:57], v[102:105], v[86:89], v[54:57]
	v_mfma_f32_16x16x32_bf16 v[58:61], v[106:109], v[86:89], v[58:61]
	v_mfma_f32_16x16x32_bf16 v[62:65], v[110:113], v[86:89], v[62:65]
	v_mfma_f32_16x16x32_bf16 v[14:17], v[114:117], v[86:89], v[14:17]
	v_mfma_f32_16x16x32_bf16 v[42:45], v[102:105], v[90:93], v[42:45]
	v_mfma_f32_16x16x32_bf16 v[66:69], v[106:109], v[90:93], v[66:69]
	v_mfma_f32_16x16x32_bf16 v[70:73], v[110:113], v[90:93], v[70:73]
	v_mfma_f32_16x16x32_bf16 v[18:21], v[114:117], v[90:93], v[18:21]
	v_mfma_f32_16x16x32_bf16 v[74:77], v[102:105], v[94:97], v[74:77]
	v_mfma_f32_16x16x32_bf16 v[78:81], v[106:109], v[94:97], v[78:81]
	v_mfma_f32_16x16x32_bf16 v[82:85], v[110:113], v[94:97], v[82:85]
	v_mfma_f32_16x16x32_bf16 v[22:25], v[114:117], v[94:97], v[22:25]
	v_mfma_f32_16x16x32_bf16 v[30:33], v[102:105], v[98:101], v[30:33]
	v_mfma_f32_16x16x32_bf16 v[34:37], v[106:109], v[98:101], v[34:37]
	v_mfma_f32_16x16x32_bf16 v[38:41], v[110:113], v[98:101], v[38:41]
	v_mfma_f32_16x16x32_bf16 v[26:29], v[114:117], v[98:101], v[26:29]
	s_setprio 0
	s_mov_b32 m0, s6
	v_lshl_add_u64 v[46:47], v[0:1], 0, s[86:87]
	s_waitcnt vmcnt(0)
	s_waitcnt vmcnt(0)
	s_barrier
; template <bool TRANS, class Epi>
; DEVI void gemm_tile(const bf16_t* __restrict__ A0, const bf16_t* __restrict__ A1, int ksplit, int lda,
;                     const bf16_t* __restrict__ Bt, int ldb, int nk, char* smem, const Epi& epi, int row0, int col0) {
;     ...
;     auto issue = [&](int kt, int buf) {
;         const bf16_t* ap = (kt < ksplit ? A0 + (size_t)kt * 64 : A1 + (size_t)(kt - ksplit) * 64) + aoff;
;         const bf16_t* bp = Bt + (size_t)kt * 64 + boff;
;         char* sa = smem + buf * 32768 + ldsoff;
;         char* sb = sa + 16384;
; #pragma unroll
;         for (int i = 0; i < 4; ++i) __builtin_amdgcn_global_load_lds((const unsigned*)(ap + (size_t)(32 * i) * lda), (unsigned*)(sa + i * 4096), 16, 0, 0);
; #pragma unroll
;         for (int i = 0; i < 4; ++i) __builtin_amdgcn_global_load_lds((const unsigned*)(bp + (size_t)(32 * i) * ldb), (unsigned*)(sb + i * 4096), 16, 0, 0);
;     };
;     __syncthreads();
;     issue(0, 0);
;     asm volatile("s_waitcnt vmcnt(0)" ::: "memory");
;     __syncthreads();
;     for (int kt = 0; kt < nk; ++kt) {
;         const int buf = kt & 1;
;         if (kt + 1 < nk) issue(kt + 1, buf ^ 1);
;         const char* sa = smem + buf * 32768;
;         const char* sb = sa + 16384;
; #pragma unroll
;         for (int kk = 0; kk < 2; ++kk) {
;             bf16x8 af[4], bfr[4];
;             const int cho = (((kk * 4 + fq) ^ (fr & 7)) << 4);
; #pragma unroll
;             for (int m = 0; m < 4; ++m) af[m] = *(const bf16x8*)(sa + (wr * 64 + 16 * m + fr) * 128 + cho);
; #pragma unroll
;             for (int n = 0; n < 4; ++n) bfr[n] = *(const bf16x8*)(sb + (wc * 64 + 16 * n + fr) * 128 + cho);
;             __builtin_amdgcn_s_setprio(1);
; #pragma unroll
;             for (int m = 0; m < 4; ++m)
; #pragma unroll
;                 for (int n = 0; n < 4; ++n)
;                     acc[m][n] = TRANS ? __builtin_amdgcn_mfma_f32_16x16x32_bf16(bfr[n], af[m], acc[m][n], 0, 0, 0)
;                                       : __builtin_amdgcn_mfma_f32_16x16x32_bf16(af[m], bfr[n], acc[m][n], 0, 0, 0);
;             __builtin_amdgcn_s_setprio(0);
;         }
;         asm volatile("s_waitcnt vmcnt(0)" ::: "memory");
;         __syncthreads();
	global_load_lds_dwordx4 v[46:47], off
	v_lshl_add_u64 v[46:47], v[0:1], 0, s[92:93]
	s_mov_b32 m0, s3
	s_nop 0
	global_load_lds_dwordx4 v[46:47], off
	v_lshl_add_u64 v[46:47], v[0:1], 0, s[94:95]
	s_mov_b32 m0, s4
	s_nop 0
	global_load_lds_dwordx4 v[46:47], off
	v_lshl_add_u64 v[46:47], v[0:1], 0, s[96:97]
	s_mov_b32 m0, s5
	s_nop 0
	global_load_lds_dwordx4 v[46:47], off
	v_lshl_add_u64 v[46:47], v[2:3], 0, s[86:87]
	s_mov_b32 m0, s7
	s_nop 0
	global_load_lds_dwordx4 v[46:47], off
	v_lshl_add_u64 v[46:47], v[2:3], 0, s[92:93]
	s_mov_b32 m0, s8
	s_nop 0
	global_load_lds_dwordx4 v[46:47], off
	v_lshl_add_u64 v[46:47], v[2:3], 0, s[94:95]
	s_mov_b32 m0, s44
	s_nop 0
	global_load_lds_dwordx4 v[46:47], off
	v_lshl_add_u64 v[46:47], v[2:3], 0, s[96:97]
	s_mov_b32 m0, s45
	s_nop 0
	global_load_lds_dwordx4 v[46:47], off
	ds_read_b128 v[86:89], v4
	ds_read_b128 v[90:93], v4 offset:2048
	ds_read_b128 v[94:97], v4 offset:4096
	ds_read_b128 v[98:101], v4 offset:6144
	ds_read_b128 v[102:105], v5 offset:16384
	ds_read_b128 v[106:109], v5 offset:18432
	ds_read_b128 v[110:113], v5 offset:20480
	ds_read_b128 v[114:117], v5 offset:22528
	s_setprio 1
	s_waitcnt lgkmcnt(0)
	v_mfma_f32_16x16x32_bf16 v[54:57], v[102:105], v[86:89], v[54:57]
	v_mfma_f32_16x16x32_bf16 v[58:61], v[106:109], v[86:89], v[58:61]
	v_mfma_f32_16x16x32_bf16 v[62:65], v[110:113], v[86:89], v[62:65]
	v_mfma_f32_16x16x32_bf16 v[14:17], v[114:117], v[86:89], v[14:17]
	v_mfma_f32_16x16x32_bf16 v[42:45], v[102:105], v[90:93], v[42:45]
	v_mfma_f32_16x16x32_bf16 v[66:69], v[106:109], v[90:93], v[66:69]
	v_mfma_f32_16x16x32_bf16 v[70:73], v[110:113], v[90:93], v[70:73]
	v_mfma_f32_16x16x32_bf16 v[18:21], v[114:117], v[90:93], v[18:21]
	v_mfma_f32_16x16x32_bf16 v[74:77], v[102:105], v[94:97], v[74:77]
	v_mfma_f32_16x16x32_bf16 v[78:81], v[106:109], v[94:97], v[78:81]
	v_mfma_f32_16x16x32_bf16 v[82:85], v[110:113], v[94:97], v[82:85]
	v_mfma_f32_16x16x32_bf16 v[22:25], v[114:117], v[94:97], v[22:25]
	v_mfma_f32_16x16x32_bf16 v[30:33], v[102:105], v[98:101], v[30:33]
	v_mfma_f32_16x16x32_bf16 v[34:37], v[106:109], v[98:101], v[34:37]
	v_mfma_f32_16x16x32_bf16 v[38:41], v[110:113], v[98:101], v[38:41]
	v_mfma_f32_16x16x32_bf16 v[26:29], v[114:117], v[98:101], v[26:29]
	s_setprio 0
	ds_read_b128 v[86:89], v6
	ds_read_b128 v[90:93], v6 offset:2048
	ds_read_b128 v[94:97], v6 offset:4096
	ds_read_b128 v[98:101], v6 offset:6144
	ds_read_b128 v[102:105], v7 offset:16384
	ds_read_b128 v[106:109], v7 offset:18432
	ds_read_b128 v[110:113], v7 offset:20480
	ds_read_b128 v[114:117], v7 offset:22528
	s_setprio 1
	s_waitcnt lgkmcnt(0)
	v_mfma_f32_16x16x32_bf16 v[54:57], v[102:105], v[86:89], v[54:57]
	v_mfma_f32_16x16x32_bf16 v[58:61], v[106:109], v[86:89], v[58:61]
	v_mfma_f32_16x16x32_bf16 v[62:65], v[110:113], v[86:89], v[62:65]
	v_mfma_f32_16x16x32_bf16 v[14:17], v[114:117], v[86:89], v[14:17]
	v_mfma_f32_16x16x32_bf16 v[42:45], v[102:105], v[90:93], v[42:45]
	v_mfma_f32_16x16x32_bf16 v[66:69], v[106:109], v[90:93], v[66:69]
	v_mfma_f32_16x16x32_bf16 v[70:73], v[110:113], v[90:93], v[70:73]
	v_mfma_f32_16x16x32_bf16 v[18:21], v[114:117], v[90:93], v[18:21]
	v_mfma_f32_16x16x32_bf16 v[74:77], v[102:105], v[94:97], v[74:77]
	v_mfma_f32_16x16x32_bf16 v[78:81], v[106:109], v[94:97], v[78:81]
	v_mfma_f32_16x16x32_bf16 v[82:85], v[110:113], v[94:97], v[82:85]
	v_mfma_f32_16x16x32_bf16 v[22:25], v[114:117], v[94:97], v[22:25]
	v_mfma_f32_16x16x32_bf16 v[30:33], v[102:105], v[98:101], v[30:33]
	v_mfma_f32_16x16x32_bf16 v[34:37], v[106:109], v[98:101], v[34:37]
	v_mfma_f32_16x16x32_bf16 v[38:41], v[110:113], v[98:101], v[38:41]
	v_mfma_f32_16x16x32_bf16 v[26:29], v[114:117], v[98:101], v[26:29]
	s_setprio 0
	s_mov_b32 m0, s19
	v_lshl_add_u64 v[46:47], v[0:1], 0, s[22:23]
	s_waitcnt vmcnt(0)
	s_waitcnt vmcnt(0)
	s_barrier
	global_load_lds_dwordx4 v[46:47], off
	v_lshl_add_u64 v[46:47], v[0:1], 0, s[34:35]
	s_mov_b32 m0, s26
	s_nop 0
	global_load_lds_dwordx4 v[46:47], off
	v_lshl_add_u64 v[46:47], v[0:1], 0, s[42:43]
	s_mov_b32 m0, s83
	s_nop 0
	global_load_lds_dwordx4 v[46:47], off
	v_lshl_add_u64 v[46:47], v[0:1], 0, s[36:37]
	s_mov_b32 m0, s18
	s_nop 0
	global_load_lds_dwordx4 v[46:47], off
	v_lshl_add_u64 v[46:47], v[2:3], 0, s[22:23]
	s_mov_b32 m0, s77
	s_nop 0
	global_load_lds_dwordx4 v[46:47], off
	v_lshl_add_u64 v[46:47], v[2:3], 0, s[34:35]
	s_mov_b32 m0, s0
	s_nop 0
	global_load_lds_dwordx4 v[46:47], off
	v_lshl_add_u64 v[46:47], v[2:3], 0, s[42:43]
	s_mov_b32 m0, s1
	s_nop 0
	global_load_lds_dwordx4 v[46:47], off
	v_lshl_add_u64 v[46:47], v[2:3], 0, s[36:37]
	s_mov_b32 m0, s2
	s_nop 0
	global_load_lds_dwordx4 v[46:47], off
	ds_read_b128 v[86:89], v4 offset:32768
	ds_read_b128 v[90:93], v4 offset:34816
	ds_read_b128 v[94:97], v4 offset:36864
	ds_read_b128 v[98:101], v4 offset:38912
	ds_read_b128 v[102:105], v5 offset:49152
	ds_read_b128 v[106:109], v5 offset:51200
	ds_read_b128 v[110:113], v5 offset:53248
	ds_read_b128 v[114:117], v5 offset:55296
	s_setprio 1
	s_waitcnt lgkmcnt(0)
; template <bool TRANS, class Epi>
; DEVI void gemm_tile(const bf16_t* __restrict__ A0, const bf16_t* __restrict__ A1, int ksplit, int lda,
;                     const bf16_t* __restrict__ Bt, int ldb, int nk, char* smem, const Epi& epi, int row0, int col0) {
;     ...
;     for (int kt = 0; kt < nk; ++kt) {
;         const int buf = kt & 1;
;         if (kt + 1 < nk) issue(kt + 1, buf ^ 1);
;         const char* sa = smem + buf * 32768;
;         const char* sb = sa + 16384;
; #pragma unroll
;         for (int kk = 0; kk < 2; ++kk) {
;             bf16x8 af[4], bfr[4];
;             const int cho = (((kk * 4 + fq) ^ (fr & 7)) << 4);
; #pragma unroll
;             for (int m = 0; m < 4; ++m) af[m] = *(const bf16x8*)(sa + (wr * 64 + 16 * m + fr) * 128 + cho);
; #pragma unroll
;             for (int n = 0; n < 4; ++n) bfr[n] = *(const bf16x8*)(sb + (wc * 64 + 16 * n + fr) * 128 + cho);
;             __builtin_amdgcn_s_setprio(1);
; #pragma unroll
;             for (int m = 0; m < 4; ++m)
; #pragma unroll
;                 for (int n = 0; n < 4; ++n)
;                     acc[m][n] = TRANS ? __builtin_amdgcn_mfma_f32_16x16x32_bf16(bfr[n], af[m], acc[m][n], 0, 0, 0)
;                                       : __builtin_amdgcn_mfma_f32_16x16x32_bf16(af[m], bfr[n], acc[m][n], 0, 0, 0);
;             __builtin_amdgcn_s_setprio(0);
;         }
;         asm volatile("s_waitcnt vmcnt(0)" ::: "memory");
;         __syncthreads();
;     }
	v_mfma_f32_16x16x32_bf16 v[54:57], v[102:105], v[86:89], v[54:57]
	v_mfma_f32_16x16x32_bf16 v[58:61], v[106:109], v[86:89], v[58:61]
	v_mfma_f32_16x16x32_bf16 v[62:65], v[110:113], v[86:89], v[62:65]
	v_mfma_f32_16x16x32_bf16 v[14:17], v[114:117], v[86:89], v[14:17]
	v_mfma_f32_16x16x32_bf16 v[42:45], v[102:105], v[90:93], v[42:45]
	v_mfma_f32_16x16x32_bf16 v[66:69], v[106:109], v[90:93], v[66:69]
	v_mfma_f32_16x16x32_bf16 v[70:73], v[110:113], v[90:93], v[70:73]
	v_mfma_f32_16x16x32_bf16 v[18:21], v[114:117], v[90:93], v[18:21]
	v_mfma_f32_16x16x32_bf16 v[74:77], v[102:105], v[94:97], v[74:77]
	v_mfma_f32_16x16x32_bf16 v[78:81], v[106:109], v[94:97], v[78:81]
	v_mfma_f32_16x16x32_bf16 v[82:85], v[110:113], v[94:97], v[82:85]
	v_mfma_f32_16x16x32_bf16 v[22:25], v[114:117], v[94:97], v[22:25]
	v_mfma_f32_16x16x32_bf16 v[30:33], v[102:105], v[98:101], v[30:33]
	v_mfma_f32_16x16x32_bf16 v[34:37], v[106:109], v[98:101], v[34:37]
	v_mfma_f32_16x16x32_bf16 v[38:41], v[110:113], v[98:101], v[38:41]
	v_mfma_f32_16x16x32_bf16 v[26:29], v[114:117], v[98:101], v[26:29]
	s_setprio 0
	ds_read_b128 v[86:89], v6 offset:32768
	ds_read_b128 v[90:93], v6 offset:34816
	ds_read_b128 v[94:97], v6 offset:36864
	ds_read_b128 v[98:101], v6 offset:38912
	ds_read_b128 v[102:105], v7 offset:49152
	ds_read_b128 v[106:109], v7 offset:51200
	ds_read_b128 v[110:113], v7 offset:53248
	ds_read_b128 v[114:117], v7 offset:55296
	s_setprio 1
	s_waitcnt lgkmcnt(0)
	v_mfma_f32_16x16x32_bf16 v[54:57], v[102:105], v[86:89], v[54:57]
	v_mfma_f32_16x16x32_bf16 v[58:61], v[106:109], v[86:89], v[58:61]
	v_mfma_f32_16x16x32_bf16 v[62:65], v[110:113], v[86:89], v[62:65]
	v_mfma_f32_16x16x32_bf16 v[14:17], v[114:117], v[86:89], v[14:17]
	v_mfma_f32_16x16x32_bf16 v[42:45], v[102:105], v[90:93], v[42:45]
	v_mfma_f32_16x16x32_bf16 v[66:69], v[106:109], v[90:93], v[66:69]
	v_mfma_f32_16x16x32_bf16 v[70:73], v[110:113], v[90:93], v[70:73]
	v_mfma_f32_16x16x32_bf16 v[18:21], v[114:117], v[90:93], v[18:21]
	v_mfma_f32_16x16x32_bf16 v[74:77], v[102:105], v[94:97], v[74:77]
	v_mfma_f32_16x16x32_bf16 v[78:81], v[106:109], v[94:97], v[78:81]
	v_mfma_f32_16x16x32_bf16 v[82:85], v[110:113], v[94:97], v[82:85]
	v_mfma_f32_16x16x32_bf16 v[22:25], v[114:117], v[94:97], v[22:25]
	v_mfma_f32_16x16x32_bf16 v[30:33], v[102:105], v[98:101], v[30:33]
	v_mfma_f32_16x16x32_bf16 v[34:37], v[106:109], v[98:101], v[34:37]
	v_mfma_f32_16x16x32_bf16 v[38:41], v[110:113], v[98:101], v[38:41]
	v_mfma_f32_16x16x32_bf16 v[26:29], v[114:117], v[98:101], v[26:29]
	s_setprio 0
	v_readfirstlane_b32 s0, v8
	v_lshl_add_u64 v[46:47], v[0:1], 0, s[14:15]
	s_mov_b32 m0, s0
	v_readfirstlane_b32 s0, v9
	s_waitcnt vmcnt(0)
	s_waitcnt vmcnt(0)
	s_barrier
	global_load_lds_dwordx4 v[46:47], off
	v_lshl_add_u64 v[46:47], v[0:1], 0, s[50:51]
	s_mov_b32 m0, s0
	v_readfirstlane_b32 s0, v10
	global_load_lds_dwordx4 v[46:47], off
	v_lshl_add_u64 v[8:9], v[0:1], 0, s[70:71]
	s_mov_b32 m0, s0
	v_readfirstlane_b32 s0, v11
	global_load_lds_dwordx4 v[8:9], off
	v_lshl_add_u64 v[0:1], v[0:1], 0, s[72:73]
	s_mov_b32 m0, s0
	v_readfirstlane_b32 s0, v12
	global_load_lds_dwordx4 v[0:1], off
	v_lshl_add_u64 v[0:1], v[2:3], 0, s[14:15]
	s_mov_b32 m0, s0
	v_readfirstlane_b32 s0, v13
	global_load_lds_dwordx4 v[0:1], off
	v_lshl_add_u64 v[0:1], v[2:3], 0, s[50:51]
	s_mov_b32 m0, s0
	s_nop 0
	global_load_lds_dwordx4 v[0:1], off
	v_lshl_add_u64 v[0:1], v[2:3], 0, s[70:71]
	s_mov_b32 m0, s44
	s_nop 0
	global_load_lds_dwordx4 v[0:1], off
	v_lshl_add_u64 v[0:1], v[2:3], 0, s[72:73]
	s_mov_b32 m0, s45
	s_nop 0
	global_load_lds_dwordx4 v[0:1], off
	ds_read_b128 v[0:3], v4
	ds_read_b128 v[8:11], v4 offset:2048
	ds_read_b128 v[86:89], v4 offset:4096
	ds_read_b128 v[90:93], v4 offset:6144
	ds_read_b128 v[94:97], v5 offset:16384
	ds_read_b128 v[98:101], v5 offset:18432
	ds_read_b128 v[102:105], v5 offset:20480
	ds_read_b128 v[106:109], v5 offset:22528
	s_setprio 1
	s_waitcnt lgkmcnt(0)
	v_mfma_f32_16x16x32_bf16 v[54:57], v[94:97], v[0:3], v[54:57]
	v_mfma_f32_16x16x32_bf16 v[58:61], v[98:101], v[0:3], v[58:61]
	v_mfma_f32_16x16x32_bf16 v[62:65], v[102:105], v[0:3], v[62:65]
	v_mfma_f32_16x16x32_bf16 v[0:3], v[106:109], v[0:3], v[14:17]
	v_mfma_f32_16x16x32_bf16 v[12:15], v[94:97], v[8:11], v[42:45]
	v_mfma_f32_16x16x32_bf16 v[42:45], v[98:101], v[8:11], v[66:69]
	v_mfma_f32_16x16x32_bf16 v[66:69], v[102:105], v[8:11], v[70:73]
	v_mfma_f32_16x16x32_bf16 v[8:11], v[106:109], v[8:11], v[18:21]
	v_mfma_f32_16x16x32_bf16 v[16:19], v[94:97], v[86:89], v[74:77]
	v_mfma_f32_16x16x32_bf16 v[70:73], v[98:101], v[86:89], v[78:81]
	v_mfma_f32_16x16x32_bf16 v[74:77], v[102:105], v[86:89], v[82:85]
	v_mfma_f32_16x16x32_bf16 v[20:23], v[106:109], v[86:89], v[22:25]
	v_mfma_f32_16x16x32_bf16 v[30:33], v[94:97], v[90:93], v[30:33]
	v_mfma_f32_16x16x32_bf16 v[34:37], v[98:101], v[90:93], v[34:37]
	v_mfma_f32_16x16x32_bf16 v[38:41], v[102:105], v[90:93], v[38:41]
	v_mfma_f32_16x16x32_bf16 v[24:27], v[106:109], v[90:93], v[26:29]
	s_setprio 0
	ds_read_b128 v[78:81], v6
	ds_read_b128 v[82:85], v6 offset:2048
	ds_read_b128 v[86:89], v6 offset:4096
	ds_read_b128 v[90:93], v6 offset:6144
	ds_read_b128 v[94:97], v7 offset:16384
	ds_read_b128 v[98:101], v7 offset:18432
	ds_read_b128 v[102:105], v7 offset:20480
	ds_read_b128 v[106:109], v7 offset:22528
	s_setprio 1
	s_waitcnt lgkmcnt(0)
	v_mfma_f32_16x16x32_bf16 v[54:57], v[94:97], v[78:81], v[54:57]
	v_mfma_f32_16x16x32_bf16 v[58:61], v[98:101], v[78:81], v[58:61]
	v_mfma_f32_16x16x32_bf16 v[62:65], v[102:105], v[78:81], v[62:65]
	v_mfma_f32_16x16x32_bf16 v[0:3], v[106:109], v[78:81], v[0:3]
	v_mfma_f32_16x16x32_bf16 v[12:15], v[94:97], v[82:85], v[12:15]
	v_mfma_f32_16x16x32_bf16 v[42:45], v[98:101], v[82:85], v[42:45]
	v_mfma_f32_16x16x32_bf16 v[66:69], v[102:105], v[82:85], v[66:69]
	v_mfma_f32_16x16x32_bf16 v[8:11], v[106:109], v[82:85], v[8:11]
	v_mfma_f32_16x16x32_bf16 v[16:19], v[94:97], v[86:89], v[16:19]
	v_mfma_f32_16x16x32_bf16 v[70:73], v[98:101], v[86:89], v[70:73]
	v_mfma_f32_16x16x32_bf16 v[74:77], v[102:105], v[86:89], v[74:77]
	v_mfma_f32_16x16x32_bf16 v[20:23], v[106:109], v[86:89], v[20:23]
	v_mfma_f32_16x16x32_bf16 v[28:31], v[94:97], v[90:93], v[30:33]
	v_mfma_f32_16x16x32_bf16 v[32:35], v[98:101], v[90:93], v[34:37]
	v_mfma_f32_16x16x32_bf16 v[36:39], v[102:105], v[90:93], v[38:41]
	v_mfma_f32_16x16x32_bf16 v[24:27], v[106:109], v[90:93], v[24:27]
	s_setprio 0
	s_waitcnt vmcnt(0)
	s_waitcnt vmcnt(0)
	s_barrier
; template <bool TRANS, class Epi>
; DEVI void gemm_tile(const bf16_t* __restrict__ A0, const bf16_t* __restrict__ A1, int ksplit, int lda,
;                     const bf16_t* __restrict__ Bt, int ldb, int nk, char* smem, const Epi& epi, int row0, int col0) {
;     ...
;     for (int kt = 0; kt < nk; ++kt) {
;         const int buf = kt & 1;
;         if (kt + 1 < nk) issue(kt + 1, buf ^ 1);
;         const char* sa = smem + buf * 32768;
;         const char* sb = sa + 16384;
; #pragma unroll
;         for (int kk = 0; kk < 2; ++kk) {
;             bf16x8 af[4], bfr[4];
;             const int cho = (((kk * 4 + fq) ^ (fr & 7)) << 4);
; #pragma unroll
;             for (int m = 0; m < 4; ++m) af[m] = *(const bf16x8*)(sa + (wr * 64 + 16 * m + fr) * 128 + cho);
; #pragma unroll
;             for (int n = 0; n < 4; ++n) bfr[n] = *(const bf16x8*)(sb + (wc * 64 + 16 * n + fr) * 128 + cho);
;             __builtin_amdgcn_s_setprio(1);
; #pragma unroll
;             for (int m = 0; m < 4; ++m)
; #pragma unroll
;                 for (int n = 0; n < 4; ++n)
;                     acc[m][n] = TRANS ? __builtin_amdgcn_mfma_f32_16x16x32_bf16(bfr[n], af[m], acc[m][n], 0, 0, 0)
;                                       : __builtin_amdgcn_mfma_f32_16x16x32_bf16(af[m], bfr[n], acc[m][n], 0, 0, 0);
;             __builtin_amdgcn_s_setprio(0);
;         }
;         asm volatile("s_waitcnt vmcnt(0)" ::: "memory");
;         __syncthreads();
;     }
;     template <int MT> DEVI void operator()(f32x4 (&acc)[MT][4], int row0, int col0, int fr, int fq) const {
; #pragma unroll
;         for (int n = 0; n < 4; ++n) {
;             const int col = col0 + 16 * n + 4 * fq;
;             const f32x4 bb = *(const f32x4*)(bfv + col);
; #pragma unroll
;             for (int m = 0; m < MT; ++m) {
;                 bf16_t* ptr = sgf + (size_t)(row0 + 16 * m + fr) * 1024 + col;
;                 const uint2 s = *(const uint2*)ptr;
	ds_read_b128 v[78:81], v5 offset:55296
	ds_read_b128 v[82:85], v5 offset:53248
	ds_read_b128 v[86:89], v5 offset:51200
	ds_read_b128 v[90:93], v5 offset:49152
	ds_read_b128 v[94:97], v4 offset:38912
	ds_read_b128 v[98:101], v4 offset:36864
	ds_read_b128 v[102:105], v4 offset:34816
	ds_read_b128 v[106:109], v4 offset:32768
	s_setprio 1
	s_waitcnt lgkmcnt(0)
	v_mfma_f32_16x16x32_bf16 v[54:57], v[90:93], v[106:109], v[54:57]
	v_mfma_f32_16x16x32_bf16 v[58:61], v[86:89], v[106:109], v[58:61]
	v_mfma_f32_16x16x32_bf16 v[62:65], v[82:85], v[106:109], v[62:65]
	v_mfma_f32_16x16x32_bf16 v[0:3], v[78:81], v[106:109], v[0:3]
	v_mfma_f32_16x16x32_bf16 v[106:109], v[90:93], v[102:105], v[12:15]
	v_mfma_f32_16x16x32_bf16 v[40:43], v[86:89], v[102:105], v[42:45]
	v_mfma_f32_16x16x32_bf16 v[66:69], v[82:85], v[102:105], v[66:69]
	v_mfma_f32_16x16x32_bf16 v[8:11], v[78:81], v[102:105], v[8:11]
	v_mfma_f32_16x16x32_bf16 v[16:19], v[90:93], v[98:101], v[16:19]
	v_mfma_f32_16x16x32_bf16 v[70:73], v[86:89], v[98:101], v[70:73]
	v_mfma_f32_16x16x32_bf16 v[74:77], v[82:85], v[98:101], v[74:77]
	v_mfma_f32_16x16x32_bf16 v[98:101], v[78:81], v[98:101], v[20:23]
	v_mfma_f32_16x16x32_bf16 v[90:93], v[90:93], v[94:97], v[28:31]
	v_mfma_f32_16x16x32_bf16 v[32:35], v[86:89], v[94:97], v[32:35]
	v_mfma_f32_16x16x32_bf16 v[82:85], v[82:85], v[94:97], v[36:39]
	v_mfma_f32_16x16x32_bf16 v[78:81], v[78:81], v[94:97], v[24:27]
	s_setprio 0
	ds_read_b128 v[12:15], v6 offset:32768
	ds_read_b128 v[20:23], v6 offset:34816
	ds_read_b128 v[86:89], v6 offset:36864
	ds_read_b128 v[94:97], v6 offset:38912
	ds_read_b128 v[102:105], v7 offset:49152
	ds_read_b128 v[110:113], v7 offset:51200
	ds_read_b128 v[114:117], v7 offset:53248
	ds_read_b128 v[118:121], v7 offset:55296
	s_setprio 1
	s_waitcnt lgkmcnt(3)
	v_mfma_f32_16x16x32_bf16 v[54:57], v[102:105], v[12:15], v[54:57]
	s_waitcnt lgkmcnt(2)
	v_mfma_f32_16x16x32_bf16 v[44:47], v[110:113], v[12:15], v[58:61]
	s_waitcnt lgkmcnt(1)
	v_mfma_f32_16x16x32_bf16 v[28:31], v[114:117], v[12:15], v[62:65]
	s_waitcnt lgkmcnt(0)
	v_mfma_f32_16x16x32_bf16 v[12:15], v[118:121], v[12:15], v[0:3]
	v_mfma_f32_16x16x32_bf16 v[60:63], v[102:105], v[20:23], v[106:109]
	v_mfma_f32_16x16x32_bf16 v[40:43], v[110:113], v[20:23], v[40:43]
	v_mfma_f32_16x16x32_bf16 v[24:27], v[114:117], v[20:23], v[66:69]
	v_mfma_f32_16x16x32_bf16 v[8:11], v[118:121], v[20:23], v[8:11]
	v_mfma_f32_16x16x32_bf16 v[64:67], v[102:105], v[86:89], v[16:19]
	v_mfma_f32_16x16x32_bf16 v[36:39], v[110:113], v[86:89], v[70:73]
	v_mfma_f32_16x16x32_bf16 v[20:23], v[114:117], v[86:89], v[74:77]
	v_mfma_f32_16x16x32_bf16 v[4:7], v[118:121], v[86:89], v[98:101]
	v_mfma_f32_16x16x32_bf16 v[68:71], v[102:105], v[94:97], v[90:93]
	v_mfma_f32_16x16x32_bf16 v[32:35], v[110:113], v[94:97], v[32:35]
	v_mfma_f32_16x16x32_bf16 v[16:19], v[114:117], v[94:97], v[82:85]
	v_mfma_f32_16x16x32_bf16 v[0:3], v[118:121], v[94:97], v[78:81]
	s_setprio 0
	v_or_b32_e32 v50, s9, v50
	v_lshl_add_u32 v76, v48, 6, v50
	v_lshlrev_b32_e32 v51, 6, v51
	v_lshlrev_b32_e32 v52, 2, v52
	v_ashrrev_i32_e32 v77, 31, v76
	v_or3_b32 v52, v51, v52, s82
	v_lshlrev_b64 v[50:51], 11, v[76:77]
	v_lshl_add_u64 v[50:51], s[54:55], 0, v[50:51]
	v_lshlrev_b32_e32 v48, 1, v52
	v_lshlrev_b32_e32 v58, 2, v52
	v_lshl_add_u64 v[50:51], v[50:51], 0, v[48:49]
	s_waitcnt vmcnt(0)
	s_barrier
	global_load_dwordx4 v[72:75], v58, s[38:39]
	global_load_dwordx2 v[52:53], v[50:51], off
	v_or_b32_e32 v122, 16, v76
	v_ashrrev_i32_e32 v123, 31, v122
	v_lshlrev_b64 v[122:123], 11, v[122:123]
	v_lshl_add_u64 v[122:123], s[54:55], 0, v[122:123]
	v_lshl_add_u64 v[122:123], v[122:123], 0, v[48:49]
	v_or_b32_e32 v124, 32, v76
	v_ashrrev_i32_e32 v125, 31, v124
	v_lshlrev_b64 v[124:125], 11, v[124:125]
	v_lshl_add_u64 v[124:125], s[54:55], 0, v[124:125]
	v_lshl_add_u64 v[124:125], v[124:125], 0, v[48:49]
	v_or_b32_e32 v126, 48, v76
	v_ashrrev_i32_e32 v127, 31, v126
	v_lshlrev_b64 v[126:127], 11, v[126:127]
	v_lshl_add_u64 v[126:127], s[54:55], 0, v[126:127]
	v_lshl_add_u64 v[126:127], v[126:127], 0, v[48:49]
	global_load_dwordx2 v[128:129], v[122:123], off
	global_load_dwordx2 v[130:131], v[124:125], off
	global_load_dwordx2 v[132:133], v[126:127], off
	global_load_dwordx2 v[134:135], v[50:51], off offset:32
	global_load_dwordx2 v[136:137], v[122:123], off offset:32
	global_load_dwordx2 v[138:139], v[124:125], off offset:32
	global_load_dwordx2 v[140:141], v[126:127], off offset:32
	global_load_dwordx2 v[142:143], v[50:51], off offset:64
	global_load_dwordx2 v[144:145], v[122:123], off offset:64
	global_load_dwordx2 v[146:147], v[124:125], off offset:64
	global_load_dwordx2 v[148:149], v[126:127], off offset:64
	global_load_dwordx2 v[150:151], v[50:51], off offset:96
	global_load_dwordx2 v[152:153], v[122:123], off offset:96
	global_load_dwordx2 v[154:155], v[124:125], off offset:96
	global_load_dwordx2 v[156:157], v[126:127], off offset:96
	global_load_dwordx4 v[160:163], v58, s[38:39] offset:64
	global_load_dwordx4 v[164:167], v58, s[38:39] offset:128
	global_load_dwordx4 v[168:171], v58, s[38:39] offset:192
	s_add_i32 s33, s33, s27
	s_add_i32 s80, s80, s81
	s_cmpk_gt_i32 s33, 0x7f
	s_waitcnt vmcnt(19)
	v_pk_fma_f32 v[54:55], v[54:55], s[76:77], v[72:73] op_sel_hi:[1,0,1]
	s_waitcnt vmcnt(0)
; DEVI unsigned pk2(float lo, float hi) { f32x2 v = {lo, hi}; bf16x2_t b = __builtin_convertvector(v, bf16x2_t); return __builtin_bit_cast(unsigned, b); }
; DEVI float bflo(unsigned u) { return __uint_as_float(u << 16); }
; DEVI float bfhi(unsigned u) { return __uint_as_float(u & 0xffff0000u); }
;     template <int MT> DEVI void operator()(f32x4 (&acc)[MT][4], int row0, int col0, int fr, int fq) const {
; #pragma unroll
;         for (int n = 0; n < 4; ++n) {
;             const int col = col0 + 16 * n + 4 * fq;
;             const f32x4 bb = *(const f32x4*)(bfv + col);
; #pragma unroll
;             for (int m = 0; m < MT; ++m) {
;                 bf16_t* ptr = sgf + (size_t)(row0 + 16 * m + fr) * 1024 + col;
;                 const uint2 s = *(const uint2*)ptr;
;                 f32x4 v = acc[m][n] * scale + bb;
;                 uint2 o; o.x = pk2(v[0] * bflo(s.x), v[1] * bfhi(s.x)); o.y = pk2(v[2] * bflo(s.y), v[3] * bfhi(s.y));
;                 *(uint2*)ptr = o;
;             }
;         }
	v_lshlrev_b32_e32 v78, 16, v52
	v_and_b32_e32 v79, 0xffff0000, v52
	v_pk_mul_f32 v[54:55], v[54:55], v[78:79]
	v_pk_fma_f32 v[56:57], v[56:57], s[76:77], v[74:75] op_sel_hi:[1,0,1]
	v_cvt_pk_bf16_f32 v52, v54, v55
	v_lshlrev_b32_e32 v54, 16, v53
	v_and_b32_e32 v55, 0xffff0000, v53
	v_pk_mul_f32 v[54:55], v[56:57], v[54:55]
	v_pk_fma_f32 v[56:57], v[62:63], s[76:77], v[74:75] op_sel_hi:[1,0,1]
	v_cvt_pk_bf16_f32 v53, v54, v55
	global_store_dwordx2 v[50:51], v[52:53], off
	v_or_b32_e32 v52, 16, v76
	v_ashrrev_i32_e32 v53, 31, v52
	v_lshlrev_b64 v[52:53], 11, v[52:53]
	v_lshl_add_u64 v[52:53], s[54:55], 0, v[52:53]
	v_lshl_add_u64 v[52:53], v[52:53], 0, v[48:49]
	v_pk_fma_f32 v[60:61], v[60:61], s[76:77], v[72:73] op_sel_hi:[1,0,1]
	v_lshlrev_b32_e32 v62, 16, v128
	v_and_b32_e32 v63, 0xffff0000, v128
	v_pk_mul_f32 v[60:61], v[60:61], v[62:63]
	v_pk_fma_f32 v[62:63], v[64:65], s[76:77], v[72:73] op_sel_hi:[1,0,1]
	v_cvt_pk_bf16_f32 v54, v60, v61
	v_lshlrev_b32_e32 v60, 16, v129
	v_and_b32_e32 v61, 0xffff0000, v129
	v_pk_mul_f32 v[56:57], v[56:57], v[60:61]
	v_pk_fma_f32 v[60:61], v[66:67], s[76:77], v[74:75] op_sel_hi:[1,0,1]
	v_cvt_pk_bf16_f32 v55, v56, v57
	global_store_dwordx2 v[52:53], v[54:55], off
	v_or_b32_e32 v54, 32, v76
	v_ashrrev_i32_e32 v55, 31, v54
	v_lshlrev_b64 v[54:55], 11, v[54:55]
	v_lshl_add_u64 v[54:55], s[54:55], 0, v[54:55]
	v_lshl_add_u64 v[54:55], v[54:55], 0, v[48:49]
	v_lshlrev_b32_e32 v64, 16, v130
	v_and_b32_e32 v65, 0xffff0000, v130
	v_pk_mul_f32 v[62:63], v[62:63], v[64:65]
	v_pk_fma_f32 v[64:65], v[68:69], s[76:77], v[72:73] op_sel_hi:[1,0,1]
	v_cvt_pk_bf16_f32 v56, v62, v63
	v_lshlrev_b32_e32 v62, 16, v131
	v_and_b32_e32 v63, 0xffff0000, v131
	v_pk_mul_f32 v[60:61], v[60:61], v[62:63]
	v_pk_fma_f32 v[62:63], v[70:71], s[76:77], v[74:75] op_sel_hi:[1,0,1]
	v_cvt_pk_bf16_f32 v57, v60, v61
	global_store_dwordx2 v[54:55], v[56:57], off
	v_or_b32_e32 v56, 48, v76
	v_ashrrev_i32_e32 v57, 31, v56
	v_lshlrev_b64 v[56:57], 11, v[56:57]
	v_lshl_add_u64 v[56:57], s[54:55], 0, v[56:57]
	v_lshl_add_u64 v[56:57], v[56:57], 0, v[48:49]
	v_lshlrev_b32_e32 v66, 16, v132
	v_and_b32_e32 v67, 0xffff0000, v132
	v_pk_mul_f32 v[64:65], v[64:65], v[66:67]
	s_nop 0
	v_cvt_pk_bf16_f32 v60, v64, v65
	v_lshlrev_b32_e32 v64, 16, v133
	v_and_b32_e32 v65, 0xffff0000, v133
	v_pk_mul_f32 v[62:63], v[62:63], v[64:65]
	s_nop 0
	v_cvt_pk_bf16_f32 v61, v62, v63
	global_store_dwordx2 v[56:57], v[60:61], off
	s_nop 0
	v_pk_fma_f32 v[46:47], v[46:47], s[76:77], v[162:163] op_sel_hi:[1,0,1]
	v_pk_fma_f32 v[44:45], v[44:45], s[76:77], v[160:161] op_sel_hi:[1,0,1]
	v_lshlrev_b32_e32 v66, 16, v134
	v_and_b32_e32 v67, 0xffff0000, v134
	v_lshlrev_b32_e32 v64, 16, v135
	v_and_b32_e32 v65, 0xffff0000, v135
	v_pk_mul_f32 v[44:45], v[44:45], v[66:67]
	v_pk_mul_f32 v[46:47], v[46:47], v[64:65]
	v_cvt_pk_bf16_f32 v44, v44, v45
	v_cvt_pk_bf16_f32 v45, v46, v47
	global_store_dwordx2 v[50:51], v[44:45], off offset:32
	v_pk_fma_f32 v[42:43], v[42:43], s[76:77], v[162:163] op_sel_hi:[1,0,1]
	v_pk_fma_f32 v[40:41], v[40:41], s[76:77], v[160:161] op_sel_hi:[1,0,1]
	v_pk_fma_f32 v[38:39], v[38:39], s[76:77], v[162:163] op_sel_hi:[1,0,1]
	v_pk_fma_f32 v[36:37], v[36:37], s[76:77], v[160:161] op_sel_hi:[1,0,1]
	v_pk_fma_f32 v[34:35], v[34:35], s[76:77], v[162:163] op_sel_hi:[1,0,1]
	v_pk_fma_f32 v[32:33], v[32:33], s[76:77], v[160:161] op_sel_hi:[1,0,1]
	v_lshlrev_b32_e32 v46, 16, v136
	v_and_b32_e32 v47, 0xffff0000, v136
	v_lshlrev_b32_e32 v44, 16, v137
	v_and_b32_e32 v45, 0xffff0000, v137
	v_pk_mul_f32 v[40:41], v[40:41], v[46:47]
	v_pk_mul_f32 v[42:43], v[42:43], v[44:45]
	v_cvt_pk_bf16_f32 v40, v40, v41
	v_cvt_pk_bf16_f32 v41, v42, v43
	global_store_dwordx2 v[52:53], v[40:41], off offset:32
	v_lshlrev_b32_e32 v42, 16, v138
	v_and_b32_e32 v43, 0xffff0000, v138
	v_lshlrev_b32_e32 v40, 16, v139
	v_and_b32_e32 v41, 0xffff0000, v139
	v_pk_mul_f32 v[36:37], v[36:37], v[42:43]
	v_pk_mul_f32 v[38:39], v[38:39], v[40:41]
	v_cvt_pk_bf16_f32 v36, v36, v37
	v_cvt_pk_bf16_f32 v37, v38, v39
	global_store_dwordx2 v[54:55], v[36:37], off offset:32
	v_lshlrev_b32_e32 v38, 16, v140
	v_and_b32_e32 v39, 0xffff0000, v140
	v_lshlrev_b32_e32 v36, 16, v141
	v_and_b32_e32 v37, 0xffff0000, v141
	v_pk_mul_f32 v[32:33], v[32:33], v[38:39]
; DEVI unsigned pk2(float lo, float hi) { f32x2 v = {lo, hi}; bf16x2_t b = __builtin_convertvector(v, bf16x2_t); return __builtin_bit_cast(unsigned, b); }
; DEVI float bflo(unsigned u) { return __uint_as_float(u << 16); }
; DEVI float bfhi(unsigned u) { return __uint_as_float(u & 0xffff0000u); }
;     template <int MT> DEVI void operator()(f32x4 (&acc)[MT][4], int row0, int col0, int fr, int fq) const {
; #pragma unroll
;         for (int n = 0; n < 4; ++n) {
;             const int col = col0 + 16 * n + 4 * fq;
;             const f32x4 bb = *(const f32x4*)(bfv + col);
; #pragma unroll
;             for (int m = 0; m < MT; ++m) {
;                 bf16_t* ptr = sgf + (size_t)(row0 + 16 * m + fr) * 1024 + col;
;                 const uint2 s = *(const uint2*)ptr;
;                 f32x4 v = acc[m][n] * scale + bb;
;                 uint2 o; o.x = pk2(v[0] * bflo(s.x), v[1] * bfhi(s.x)); o.y = pk2(v[2] * bflo(s.y), v[3] * bfhi(s.y));
;                 *(uint2*)ptr = o;
;             }
;         }
	v_pk_mul_f32 v[34:35], v[34:35], v[36:37]
	v_cvt_pk_bf16_f32 v32, v32, v33
	v_cvt_pk_bf16_f32 v33, v34, v35
	global_store_dwordx2 v[56:57], v[32:33], off offset:32
	s_nop 0
	v_pk_fma_f32 v[30:31], v[30:31], s[76:77], v[166:167] op_sel_hi:[1,0,1]
	v_pk_fma_f32 v[28:29], v[28:29], s[76:77], v[164:165] op_sel_hi:[1,0,1]
	v_lshlrev_b32_e32 v38, 16, v142
	v_and_b32_e32 v39, 0xffff0000, v142
	v_lshlrev_b32_e32 v36, 16, v143
	v_and_b32_e32 v37, 0xffff0000, v143
	v_pk_mul_f32 v[28:29], v[28:29], v[38:39]
	v_pk_mul_f32 v[30:31], v[30:31], v[36:37]
	v_cvt_pk_bf16_f32 v28, v28, v29
	v_cvt_pk_bf16_f32 v29, v30, v31
	global_store_dwordx2 v[50:51], v[28:29], off offset:64
	v_pk_fma_f32 v[26:27], v[26:27], s[76:77], v[166:167] op_sel_hi:[1,0,1]
	v_pk_fma_f32 v[24:25], v[24:25], s[76:77], v[164:165] op_sel_hi:[1,0,1]
	v_pk_fma_f32 v[22:23], v[22:23], s[76:77], v[166:167] op_sel_hi:[1,0,1]
	v_pk_fma_f32 v[20:21], v[20:21], s[76:77], v[164:165] op_sel_hi:[1,0,1]
	v_pk_fma_f32 v[18:19], v[18:19], s[76:77], v[166:167] op_sel_hi:[1,0,1]
	v_pk_fma_f32 v[16:17], v[16:17], s[76:77], v[164:165] op_sel_hi:[1,0,1]
	v_lshlrev_b32_e32 v30, 16, v144
	v_and_b32_e32 v31, 0xffff0000, v144
	v_lshlrev_b32_e32 v28, 16, v145
	v_and_b32_e32 v29, 0xffff0000, v145
	v_pk_mul_f32 v[24:25], v[24:25], v[30:31]
	v_pk_mul_f32 v[26:27], v[26:27], v[28:29]
	v_cvt_pk_bf16_f32 v24, v24, v25
	v_cvt_pk_bf16_f32 v25, v26, v27
	global_store_dwordx2 v[52:53], v[24:25], off offset:64
	v_lshlrev_b32_e32 v26, 16, v146
	v_and_b32_e32 v27, 0xffff0000, v146
	v_lshlrev_b32_e32 v24, 16, v147
	v_and_b32_e32 v25, 0xffff0000, v147
	v_pk_mul_f32 v[20:21], v[20:21], v[26:27]
	v_pk_mul_f32 v[22:23], v[22:23], v[24:25]
	v_cvt_pk_bf16_f32 v20, v20, v21
	v_cvt_pk_bf16_f32 v21, v22, v23
	global_store_dwordx2 v[54:55], v[20:21], off offset:64
	v_lshlrev_b32_e32 v22, 16, v148
	v_and_b32_e32 v23, 0xffff0000, v148
	v_lshlrev_b32_e32 v20, 16, v149
	v_and_b32_e32 v21, 0xffff0000, v149
	v_pk_mul_f32 v[16:17], v[16:17], v[22:23]
	v_pk_mul_f32 v[18:19], v[18:19], v[20:21]
	v_cvt_pk_bf16_f32 v16, v16, v17
	v_cvt_pk_bf16_f32 v17, v18, v19
	global_store_dwordx2 v[56:57], v[16:17], off offset:64
	s_nop 0
	v_pk_fma_f32 v[14:15], v[14:15], s[76:77], v[170:171] op_sel_hi:[1,0,1]
	v_pk_fma_f32 v[12:13], v[12:13], s[76:77], v[168:169] op_sel_hi:[1,0,1]
	v_lshlrev_b32_e32 v22, 16, v150
	v_and_b32_e32 v23, 0xffff0000, v150
	v_lshlrev_b32_e32 v20, 16, v151
	v_and_b32_e32 v21, 0xffff0000, v151
	v_pk_mul_f32 v[12:13], v[12:13], v[22:23]
	v_pk_mul_f32 v[14:15], v[14:15], v[20:21]
	v_cvt_pk_bf16_f32 v12, v12, v13
	v_cvt_pk_bf16_f32 v13, v14, v15
	global_store_dwordx2 v[50:51], v[12:13], off offset:96
	v_pk_fma_f32 v[10:11], v[10:11], s[76:77], v[170:171] op_sel_hi:[1,0,1]
	v_pk_fma_f32 v[8:9], v[8:9], s[76:77], v[168:169] op_sel_hi:[1,0,1]
	v_pk_fma_f32 v[6:7], v[6:7], s[76:77], v[170:171] op_sel_hi:[1,0,1]
	v_pk_fma_f32 v[4:5], v[4:5], s[76:77], v[168:169] op_sel_hi:[1,0,1]
	v_pk_fma_f32 v[2:3], v[2:3], s[76:77], v[170:171] op_sel_hi:[1,0,1]
	v_pk_fma_f32 v[0:1], v[0:1], s[76:77], v[168:169] op_sel_hi:[1,0,1]
	v_lshlrev_b32_e32 v14, 16, v152
	v_and_b32_e32 v15, 0xffff0000, v152
	v_lshlrev_b32_e32 v12, 16, v153
	v_and_b32_e32 v13, 0xffff0000, v153
	v_pk_mul_f32 v[8:9], v[8:9], v[14:15]
	v_pk_mul_f32 v[10:11], v[10:11], v[12:13]
	v_cvt_pk_bf16_f32 v8, v8, v9
	v_cvt_pk_bf16_f32 v9, v10, v11
	global_store_dwordx2 v[52:53], v[8:9], off offset:96
	v_lshlrev_b32_e32 v10, 16, v154
	v_and_b32_e32 v11, 0xffff0000, v154
	v_lshlrev_b32_e32 v8, 16, v155
	v_and_b32_e32 v9, 0xffff0000, v155
	v_pk_mul_f32 v[4:5], v[4:5], v[10:11]
	v_pk_mul_f32 v[6:7], v[6:7], v[8:9]
	v_cvt_pk_bf16_f32 v4, v4, v5
	v_cvt_pk_bf16_f32 v5, v6, v7
	global_store_dwordx2 v[54:55], v[4:5], off offset:96
	v_lshlrev_b32_e32 v6, 16, v156
	v_and_b32_e32 v7, 0xffff0000, v156
	v_lshlrev_b32_e32 v4, 16, v157
	v_and_b32_e32 v5, 0xffff0000, v157
	v_pk_mul_f32 v[0:1], v[0:1], v[6:7]
	v_pk_mul_f32 v[2:3], v[2:3], v[4:5]
	v_cvt_pk_bf16_f32 v0, v0, v1
	v_cvt_pk_bf16_f32 v1, v2, v3
	global_store_dwordx2 v[56:57], v[0:1], off offset:96
	s_cbranch_scc0 .LBB0_596
	v_readlane_b32 s92, v230, 40
	v_readlane_b32 s80, v230, 35
	v_readlane_b32 s82, v230, 37
	v_readlane_b32 s86, v230, 42
	v_readlane_b32 s93, v230, 41
	v_readlane_b32 s81, v230, 36
	v_readlane_b32 s83, v230, 38
